# tile scheduler division by the (always 8) group size replaced by shift/mask; fc2 epilogue issues both residual row-batches' loads together
# speedup vs baseline: 1.0027x; 1.0027x over previous
.LBB0_98:
	s_ashr_i32 s0, s20, 3
	s_add_i32 s0, s24, s0
	s_ashr_i32 s1, s0, 31
	s_lshr_b32 s1, s1, 27
	s_add_i32 s1, s0, s1
	s_ashr_i32 s20, s1, 5
	s_lshl_b32 s20, s20, 3
	s_andn2_b32 s1, s1, 31
	s_sub_i32 s1, s0, s1
	s_ashr_i32 s0, s1, 3
	s_and_b32 s1, s1, 7
	s_add_i32 s42, s20, s1

.LBB0_100:
	s_add_u32 s21, s48, 0xfff00080
	s_addc_u32 s28, s49, -1
	s_add_i32 s60, 0, 0x10000
	v_add_u32_e32 v124, s60, v175
	ds_read_b128 v[112:115], v124
	ds_read_b128 v[116:119], v124 offset:1024
	ds_read_b128 v[120:123], v124 offset:2048
	ds_read_b128 v[124:127], v124 offset:3072
	s_cmp_eq_u32 s20, 60
	s_cselect_b32 s51, s43, s28
	s_cselect_b32 s50, s24, s21
	s_cselect_b32 s29, s1, vcc_hi
	s_cselect_b32 s28, s25, vcc_lo
	v_lshl_add_u64 v[184:185], s[48:49], 0, v[158:159]
	s_add_i32 m0, s55, 0xc000
	ds_read_b128 v[128:131], v199
	ds_read_b128 v[132:135], v199 offset:1024
	ds_read_b128 v[162:165], v199 offset:2048
	ds_read_b128 v[166:169], v199 offset:3072
	ds_read_b128 v[170:173], v199 offset:4096
	ds_read_b128 v[200:203], v199 offset:5120
	ds_read_b128 v[204:207], v199 offset:6144
	ds_read_b128 v[208:211], v199 offset:7168
	global_load_lds_dwordx4 v[184:185], off
	v_lshl_add_u64 v[184:185], s[48:49], 0, v[160:161]
	s_add_i32 m0, s55, 0xe000
	s_nop 0
	global_load_lds_dwordx4 v[184:185], off
	s_waitcnt lgkmcnt(8)
	s_barrier
	s_waitcnt lgkmcnt(0)
	s_setprio 1
	s_waitcnt lgkmcnt(0)
	v_mfma_f32_16x16x32_bf16 v[148:151], v[112:115], v[128:131], v[148:151]
	v_mfma_f32_16x16x32_bf16 v[144:147], v[120:123], v[128:131], v[144:147]
	v_mfma_f32_16x16x32_bf16 v[108:111], v[112:115], v[162:165], v[108:111]
	v_mfma_f32_16x16x32_bf16 v[104:107], v[120:123], v[162:165], v[104:107]
	v_mfma_f32_16x16x32_bf16 v[92:95], v[112:115], v[170:173], v[92:95]
	v_mfma_f32_16x16x32_bf16 v[88:91], v[120:123], v[170:173], v[88:91]
	v_mfma_f32_16x16x32_bf16 v[76:79], v[112:115], v[204:207], v[76:79]
	v_mfma_f32_16x16x32_bf16 v[72:75], v[120:123], v[204:207], v[72:75]
	v_mfma_f32_16x16x32_bf16 v[148:151], v[116:119], v[132:135], v[148:151]
	v_mfma_f32_16x16x32_bf16 v[144:147], v[124:127], v[132:135], v[144:147]
	v_mfma_f32_16x16x32_bf16 v[108:111], v[116:119], v[166:169], v[108:111]
	v_mfma_f32_16x16x32_bf16 v[104:107], v[124:127], v[166:169], v[104:107]
	v_mfma_f32_16x16x32_bf16 v[92:95], v[116:119], v[200:203], v[92:95]
	v_mfma_f32_16x16x32_bf16 v[88:91], v[124:127], v[200:203], v[88:91]
	v_mfma_f32_16x16x32_bf16 v[76:79], v[116:119], v[208:211], v[76:79]
	v_mfma_f32_16x16x32_bf16 v[72:75], v[124:127], v[208:211], v[72:75]
	s_setprio 0
	s_barrier
	s_add_i32 s21, 0, 0x14000
	v_add_u32_e32 v184, s21, v175
	s_add_i32 s60, s60, s54
	ds_read_b128 v[212:215], v184
	ds_read_b128 v[216:219], v184 offset:1024
	ds_read_b128 v[232:235], v184 offset:2048
	ds_read_b128 v[236:239], v184 offset:3072
	v_lshl_add_u64 v[184:185], s[28:29], 0, v[176:177]
	s_mov_b32 m0, s60
	v_lshl_add_u64 v[192:193], s[28:29], 0, v[152:153]
	global_load_lds_dwordx4 v[184:185], off
	s_add_i32 m0, s60, 0x2000
	s_nop 0
	global_load_lds_dwordx4 v[192:193], off
	s_barrier
	s_waitcnt lgkmcnt(0)
	s_setprio 1
	s_waitcnt lgkmcnt(0)
	v_mfma_f32_16x16x32_bf16 v[140:143], v[212:215], v[128:131], v[140:143]
	v_mfma_f32_16x16x32_bf16 v[100:103], v[212:215], v[162:165], v[100:103]
	v_mfma_f32_16x16x32_bf16 v[96:99], v[232:235], v[162:165], v[96:99]
	v_mfma_f32_16x16x32_bf16 v[84:87], v[212:215], v[170:173], v[84:87]
	v_mfma_f32_16x16x32_bf16 v[80:83], v[232:235], v[170:173], v[80:83]
	v_mfma_f32_16x16x32_bf16 v[68:71], v[212:215], v[204:207], v[68:71]
	v_mfma_f32_16x16x32_bf16 v[64:67], v[232:235], v[204:207], v[64:67]
	v_mfma_f32_16x16x32_bf16 v[140:143], v[216:219], v[132:135], v[140:143]
	v_mfma_f32_16x16x32_bf16 v[128:131], v[232:235], v[128:131], v[136:139]
	v_mfma_f32_16x16x32_bf16 v[100:103], v[216:219], v[166:169], v[100:103]
	v_mfma_f32_16x16x32_bf16 v[96:99], v[236:239], v[166:169], v[96:99]
	v_mfma_f32_16x16x32_bf16 v[84:87], v[216:219], v[200:203], v[84:87]
	v_mfma_f32_16x16x32_bf16 v[80:83], v[236:239], v[200:203], v[80:83]
	v_mfma_f32_16x16x32_bf16 v[68:71], v[216:219], v[208:211], v[68:71]
	v_mfma_f32_16x16x32_bf16 v[64:67], v[236:239], v[208:211], v[64:67]
	v_mfma_f32_16x16x32_bf16 v[128:131], v[236:239], v[132:135], v[128:131]
	s_setprio 0
	s_mov_b32 m0, s55
	v_lshl_add_u64 v[194:195], s[50:51], 0, v[156:157]
	s_barrier
	ds_read_b128 v[132:135], v199 offset:16384
	ds_read_b128 v[136:139], v199 offset:17408
	ds_read_b128 v[162:165], v199 offset:18432
	ds_read_b128 v[166:169], v199 offset:19456
	ds_read_b128 v[170:173], v199 offset:20480
	ds_read_b128 v[200:203], v199 offset:21504
	ds_read_b128 v[204:207], v199 offset:22528
	ds_read_b128 v[208:211], v199 offset:23552
	global_load_lds_dwordx4 v[194:195], off
	v_lshl_add_u64 v[240:241], s[50:51], 0, v[154:155]
	s_mov_b32 m0, s56
	s_nop 0
	global_load_lds_dwordx4 v[240:241], off
	s_barrier
	s_waitcnt lgkmcnt(0)
	s_setprio 1
	s_waitcnt lgkmcnt(0)
	v_mfma_f32_16x16x32_bf16 v[60:63], v[112:115], v[132:135], v[60:63]
	v_mfma_f32_16x16x32_bf16 v[56:59], v[120:123], v[132:135], v[56:59]
	v_mfma_f32_16x16x32_bf16 v[44:47], v[112:115], v[162:165], v[44:47]
	v_mfma_f32_16x16x32_bf16 v[40:43], v[120:123], v[162:165], v[40:43]
	v_mfma_f32_16x16x32_bf16 v[28:31], v[112:115], v[170:173], v[28:31]
	v_mfma_f32_16x16x32_bf16 v[24:27], v[120:123], v[170:173], v[24:27]
	v_mfma_f32_16x16x32_bf16 v[12:15], v[112:115], v[204:207], v[12:15]
	v_mfma_f32_16x16x32_bf16 v[8:11], v[120:123], v[204:207], v[8:11]
	v_mfma_f32_16x16x32_bf16 v[60:63], v[116:119], v[136:139], v[60:63]
	v_mfma_f32_16x16x32_bf16 v[56:59], v[124:127], v[136:139], v[56:59]
	v_mfma_f32_16x16x32_bf16 v[44:47], v[116:119], v[166:169], v[44:47]
	v_mfma_f32_16x16x32_bf16 v[40:43], v[124:127], v[166:169], v[40:43]
	v_mfma_f32_16x16x32_bf16 v[28:31], v[116:119], v[200:203], v[28:31]
	v_mfma_f32_16x16x32_bf16 v[24:27], v[124:127], v[200:203], v[24:27]
	v_mfma_f32_16x16x32_bf16 v[12:15], v[116:119], v[208:211], v[12:15]
	v_mfma_f32_16x16x32_bf16 v[8:11], v[124:127], v[208:211], v[8:11]
	s_setprio 0
	s_barrier
	s_add_u32 s60, s28, 0x100000
	s_addc_u32 s61, s29, 0
	s_add_i32 s21, s21, s54
	v_lshl_add_u64 v[112:113], s[60:61], 0, v[176:177]
	s_mov_b32 m0, s21
	s_nop 0
	global_load_lds_dwordx4 v[112:113], off
	v_lshl_add_u64 v[112:113], s[60:61], 0, v[152:153]
	s_add_i32 m0, s21, 0x2000
	s_nop 0
	global_load_lds_dwordx4 v[112:113], off
	s_waitcnt vmcnt(6)
	s_barrier
	s_setprio 1
	v_mfma_f32_16x16x32_bf16 v[52:55], v[212:215], v[132:135], v[52:55]
	v_mfma_f32_16x16x32_bf16 v[48:51], v[232:235], v[132:135], v[48:51]
	v_mfma_f32_16x16x32_bf16 v[36:39], v[212:215], v[162:165], v[36:39]
	v_mfma_f32_16x16x32_bf16 v[32:35], v[232:235], v[162:165], v[32:35]
	v_mfma_f32_16x16x32_bf16 v[20:23], v[212:215], v[170:173], v[20:23]
	v_mfma_f32_16x16x32_bf16 v[16:19], v[232:235], v[170:173], v[16:19]
	v_mfma_f32_16x16x32_bf16 v[4:7], v[212:215], v[204:207], v[4:7]
	v_mfma_f32_16x16x32_bf16 v[0:3], v[232:235], v[204:207], v[0:3]
	v_mfma_f32_16x16x32_bf16 v[52:55], v[216:219], v[136:139], v[52:55]
	v_mfma_f32_16x16x32_bf16 v[48:51], v[236:239], v[136:139], v[48:51]
	v_mfma_f32_16x16x32_bf16 v[36:39], v[216:219], v[166:169], v[36:39]
	v_mfma_f32_16x16x32_bf16 v[32:35], v[236:239], v[166:169], v[32:35]
	v_mfma_f32_16x16x32_bf16 v[20:23], v[216:219], v[200:203], v[20:23]
	v_mfma_f32_16x16x32_bf16 v[16:19], v[236:239], v[200:203], v[16:19]
	v_mfma_f32_16x16x32_bf16 v[4:7], v[216:219], v[208:211], v[4:7]
	v_mfma_f32_16x16x32_bf16 v[0:3], v[236:239], v[208:211], v[0:3]
	s_setprio 0
	s_add_i32 s21, 0, 0x18000
	v_add_u32_e32 v124, s21, v175
	s_barrier
	ds_read_b128 v[112:115], v124
	ds_read_b128 v[116:119], v124 offset:1024
	ds_read_b128 v[120:123], v124 offset:2048
	ds_read_b128 v[124:127], v124 offset:3072
	s_add_u32 s50, s50, 0x100000
	s_addc_u32 s51, s51, 0
	s_mov_b32 m0, s57
	v_lshl_add_u64 v[212:213], s[50:51], 0, v[156:157]
	ds_read_b128 v[132:135], v199 offset:32768
	ds_read_b128 v[136:139], v199 offset:33792
	ds_read_b128 v[162:165], v199 offset:34816
	ds_read_b128 v[166:169], v199 offset:35840
	ds_read_b128 v[170:173], v199 offset:36864
	ds_read_b128 v[200:203], v199 offset:37888
	ds_read_b128 v[204:207], v199 offset:38912
	ds_read_b128 v[208:211], v199 offset:39936
	global_load_lds_dwordx4 v[212:213], off
	v_lshl_add_u64 v[212:213], s[50:51], 0, v[154:155]
	s_mov_b32 m0, s58
	s_nop 0
	global_load_lds_dwordx4 v[212:213], off
	s_waitcnt lgkmcnt(8)
	s_barrier
	s_waitcnt lgkmcnt(0)
	s_setprio 1
	s_waitcnt lgkmcnt(0)
	v_mfma_f32_16x16x32_bf16 v[148:151], v[112:115], v[132:135], v[148:151]
	v_mfma_f32_16x16x32_bf16 v[144:147], v[120:123], v[132:135], v[144:147]
	v_mfma_f32_16x16x32_bf16 v[108:111], v[112:115], v[162:165], v[108:111]
	v_mfma_f32_16x16x32_bf16 v[104:107], v[120:123], v[162:165], v[104:107]
	v_mfma_f32_16x16x32_bf16 v[92:95], v[112:115], v[170:173], v[92:95]
	v_mfma_f32_16x16x32_bf16 v[88:91], v[120:123], v[170:173], v[88:91]
	v_mfma_f32_16x16x32_bf16 v[76:79], v[112:115], v[204:207], v[76:79]
	v_mfma_f32_16x16x32_bf16 v[72:75], v[120:123], v[204:207], v[72:75]
	v_mfma_f32_16x16x32_bf16 v[148:151], v[116:119], v[136:139], v[148:151]
	v_mfma_f32_16x16x32_bf16 v[144:147], v[124:127], v[136:139], v[144:147]
	v_mfma_f32_16x16x32_bf16 v[108:111], v[116:119], v[166:169], v[108:111]
	v_mfma_f32_16x16x32_bf16 v[104:107], v[124:127], v[166:169], v[104:107]
	v_mfma_f32_16x16x32_bf16 v[92:95], v[116:119], v[200:203], v[92:95]
	v_mfma_f32_16x16x32_bf16 v[88:91], v[124:127], v[200:203], v[88:91]
	v_mfma_f32_16x16x32_bf16 v[76:79], v[116:119], v[208:211], v[76:79]
	v_mfma_f32_16x16x32_bf16 v[72:75], v[124:127], v[208:211], v[72:75]
	s_setprio 0
	s_barrier
	s_add_i32 s50, 0, 0x1c000
	s_add_i32 s21, s21, s54
	v_add_u32_e32 v231, s50, v175
	v_lshl_add_u64 v[184:185], v[184:185], 0, s[52:53]
	s_mov_b32 m0, s21
	ds_read_b128 v[212:215], v231
	ds_read_b128 v[216:219], v231 offset:1024
	ds_read_b128 v[232:235], v231 offset:2048
	ds_read_b128 v[236:239], v231 offset:3072
	global_load_lds_dwordx4 v[184:185], off
	v_lshl_add_u64 v[184:185], v[192:193], 0, s[52:53]
	s_add_i32 m0, s21, 0x2000
	s_nop 0
	global_load_lds_dwordx4 v[184:185], off
	s_barrier
	s_waitcnt lgkmcnt(0)
	s_setprio 1
	s_waitcnt lgkmcnt(0)
	v_mfma_f32_16x16x32_bf16 v[140:143], v[212:215], v[132:135], v[140:143]
	v_mfma_f32_16x16x32_bf16 v[128:131], v[232:235], v[132:135], v[128:131]
	v_mfma_f32_16x16x32_bf16 v[100:103], v[212:215], v[162:165], v[100:103]
	v_mfma_f32_16x16x32_bf16 v[96:99], v[232:235], v[162:165], v[96:99]
	v_mfma_f32_16x16x32_bf16 v[84:87], v[212:215], v[170:173], v[84:87]
	v_mfma_f32_16x16x32_bf16 v[80:83], v[232:235], v[170:173], v[80:83]
	v_mfma_f32_16x16x32_bf16 v[68:71], v[212:215], v[204:207], v[68:71]
	v_mfma_f32_16x16x32_bf16 v[64:67], v[232:235], v[204:207], v[64:67]
	v_mfma_f32_16x16x32_bf16 v[140:143], v[216:219], v[136:139], v[140:143]
	v_mfma_f32_16x16x32_bf16 v[136:139], v[236:239], v[136:139], v[128:131]
	v_mfma_f32_16x16x32_bf16 v[100:103], v[216:219], v[166:169], v[100:103]
	v_mfma_f32_16x16x32_bf16 v[96:99], v[236:239], v[166:169], v[96:99]
	v_mfma_f32_16x16x32_bf16 v[84:87], v[216:219], v[200:203], v[84:87]
	v_mfma_f32_16x16x32_bf16 v[80:83], v[236:239], v[200:203], v[80:83]
	v_mfma_f32_16x16x32_bf16 v[68:71], v[216:219], v[208:211], v[68:71]
	v_mfma_f32_16x16x32_bf16 v[64:67], v[236:239], v[208:211], v[64:67]
	s_setprio 0
	s_mov_b32 m0, s7
	v_lshl_add_u64 v[184:185], v[194:195], 0, s[52:53]
	s_barrier
	ds_read_b128 v[128:131], v199 offset:49152
	ds_read_b128 v[132:135], v199 offset:50176
	ds_read_b128 v[162:165], v199 offset:51200
	ds_read_b128 v[166:169], v199 offset:52224
	ds_read_b128 v[170:173], v199 offset:53248
	ds_read_b128 v[200:203], v199 offset:54272
	ds_read_b128 v[204:207], v199 offset:55296
	ds_read_b128 v[208:211], v199 offset:56320
	global_load_lds_dwordx4 v[184:185], off
	v_lshl_add_u64 v[184:185], v[240:241], 0, s[52:53]
	s_mov_b32 m0, s15
	s_nop 0
	global_load_lds_dwordx4 v[184:185], off
	s_barrier
	s_waitcnt lgkmcnt(0)
	s_setprio 1
	s_waitcnt lgkmcnt(0)
	v_mfma_f32_16x16x32_bf16 v[60:63], v[112:115], v[128:131], v[60:63]
	v_mfma_f32_16x16x32_bf16 v[56:59], v[120:123], v[128:131], v[56:59]
	v_mfma_f32_16x16x32_bf16 v[44:47], v[112:115], v[162:165], v[44:47]
	v_mfma_f32_16x16x32_bf16 v[40:43], v[120:123], v[162:165], v[40:43]
	v_mfma_f32_16x16x32_bf16 v[28:31], v[112:115], v[170:173], v[28:31]
	v_mfma_f32_16x16x32_bf16 v[24:27], v[120:123], v[170:173], v[24:27]
	v_mfma_f32_16x16x32_bf16 v[12:15], v[112:115], v[204:207], v[12:15]
	v_mfma_f32_16x16x32_bf16 v[8:11], v[120:123], v[204:207], v[8:11]
	v_mfma_f32_16x16x32_bf16 v[60:63], v[116:119], v[132:135], v[60:63]
	v_mfma_f32_16x16x32_bf16 v[56:59], v[124:127], v[132:135], v[56:59]
	v_mfma_f32_16x16x32_bf16 v[44:47], v[116:119], v[166:169], v[44:47]
	v_mfma_f32_16x16x32_bf16 v[40:43], v[124:127], v[166:169], v[40:43]
	v_mfma_f32_16x16x32_bf16 v[28:31], v[116:119], v[200:203], v[28:31]
	v_mfma_f32_16x16x32_bf16 v[24:27], v[124:127], v[200:203], v[24:27]
	v_mfma_f32_16x16x32_bf16 v[12:15], v[116:119], v[208:211], v[12:15]
	v_mfma_f32_16x16x32_bf16 v[8:11], v[124:127], v[208:211], v[8:11]
	s_setprio 0
	s_barrier
	s_add_u32 s28, s28, 0x100080
	s_addc_u32 s29, s29, 0
	s_add_i32 s21, s50, s54
	v_lshl_add_u64 v[112:113], s[28:29], 0, v[176:177]
	s_mov_b32 m0, s21
	s_nop 0
	global_load_lds_dwordx4 v[112:113], off
	v_lshl_add_u64 v[112:113], s[28:29], 0, v[152:153]
	s_add_i32 m0, s21, 0x2000
	s_nop 0
	global_load_lds_dwordx4 v[112:113], off
	s_waitcnt vmcnt(6)
	s_barrier
	s_setprio 1
	v_mfma_f32_16x16x32_bf16 v[52:55], v[212:215], v[128:131], v[52:55]
	v_mfma_f32_16x16x32_bf16 v[48:51], v[232:235], v[128:131], v[48:51]
	v_mfma_f32_16x16x32_bf16 v[36:39], v[212:215], v[162:165], v[36:39]
	v_mfma_f32_16x16x32_bf16 v[32:35], v[232:235], v[162:165], v[32:35]
	v_mfma_f32_16x16x32_bf16 v[20:23], v[212:215], v[170:173], v[20:23]
	v_mfma_f32_16x16x32_bf16 v[16:19], v[232:235], v[170:173], v[16:19]
	v_mfma_f32_16x16x32_bf16 v[4:7], v[212:215], v[204:207], v[4:7]
	v_mfma_f32_16x16x32_bf16 v[0:3], v[232:235], v[204:207], v[0:3]
	v_mfma_f32_16x16x32_bf16 v[52:55], v[216:219], v[132:135], v[52:55]
	v_mfma_f32_16x16x32_bf16 v[48:51], v[236:239], v[132:135], v[48:51]
	v_mfma_f32_16x16x32_bf16 v[36:39], v[216:219], v[166:169], v[36:39]
	v_mfma_f32_16x16x32_bf16 v[32:35], v[236:239], v[166:169], v[32:35]
	v_mfma_f32_16x16x32_bf16 v[20:23], v[216:219], v[200:203], v[20:23]
	v_mfma_f32_16x16x32_bf16 v[16:19], v[236:239], v[200:203], v[16:19]
	v_mfma_f32_16x16x32_bf16 v[4:7], v[216:219], v[208:211], v[4:7]
	v_mfma_f32_16x16x32_bf16 v[0:3], v[236:239], v[208:211], v[0:3]
	s_setprio 0
	s_add_i32 s20, s20, 2
	s_add_u32 s48, s48, 0x100
	s_addc_u32 s49, s49, 0
	s_add_u32 vcc_lo, vcc_lo, 0x100
	s_addc_u32 vcc_hi, vcc_hi, 0
	s_cmp_gt_u32 s20, 61
	s_barrier
	s_cbranch_scc0 .LBB0_100
	v_lshl_or_b32 v162, s34, 8, v198
	v_lshl_add_u32 v166, s2, 8, v174
	v_ashrrev_i32_e32 v163, 31, v162
	v_lshlrev_b64 v[184:185], 1, v[162:163]
	v_ashrrev_i32_e32 v167, 31, v166
	v_lshl_add_u64 v[164:165], s[68:69], 0, v[184:185]
	v_lshlrev_b64 v[192:193], 11, v[166:167]
	v_lshl_add_u64 v[112:113], v[164:165], 0, v[192:193]
	global_load_dwordx4 v[200:203], v[112:113], off
	global_load_dwordx4 v[204:207], v[112:113], off offset:256
	v_or_b32_e32 v172, 16, v166
	v_ashrrev_i32_e32 v173, 31, v172
	v_lshlrev_b64 v[112:113], 11, v[172:173]
	v_or_b32_e32 v170, 32, v166
	v_lshl_add_u64 v[112:113], v[164:165], 0, v[112:113]
	v_ashrrev_i32_e32 v171, 31, v170
	global_load_dwordx4 v[132:135], v[112:113], off
	global_load_dwordx4 v[128:131], v[112:113], off offset:256
	v_lshlrev_b64 v[112:113], 11, v[170:171]
	v_or_b32_e32 v168, 48, v166
	v_lshl_add_u64 v[112:113], v[164:165], 0, v[112:113]
	v_ashrrev_i32_e32 v169, 31, v168
	global_load_dwordx4 v[124:127], v[112:113], off
	global_load_dwordx4 v[120:123], v[112:113], off offset:256
	v_lshlrev_b64 v[112:113], 11, v[168:169]
	v_lshl_add_u64 v[112:113], v[164:165], 0, v[112:113]
	global_load_dwordx4 v[116:119], v[112:113], off
	s_nop 0
	global_load_dwordx4 v[112:115], v[112:113], off offset:256
	v_add_u32_e32 v214, 0x80, v166
	v_ashrrev_i32_e32 v215, 31, v214
	v_lshlrev_b64 v[214:215], 11, v[214:215]
	v_lshl_add_u64 v[214:215], v[164:165], 0, v[214:215]
	global_load_dwordx4 v[208:211], v[214:215], off
	s_nop 0
	global_load_dwordx4 v[212:215], v[214:215], off offset:256
	v_add_u32_e32 v234, 0x90, v166
	v_ashrrev_i32_e32 v235, 31, v234
	v_lshlrev_b64 v[234:235], 11, v[234:235]
	v_lshl_add_u64 v[234:235], v[164:165], 0, v[234:235]
	global_load_dwordx4 v[216:219], v[234:235], off
	s_nop 0
	global_load_dwordx4 v[232:235], v[234:235], off offset:256
	v_add_u32_e32 v242, 0xa0, v166
	v_ashrrev_i32_e32 v243, 31, v242
	v_lshlrev_b64 v[242:243], 11, v[242:243]
	v_lshl_add_u64 v[242:243], v[164:165], 0, v[242:243]
	global_load_dwordx4 v[236:239], v[242:243], off
	s_nop 0
	global_load_dwordx4 v[240:243], v[242:243], off offset:256
	v_add_u32_e32 v250, 0xb0, v166
	v_ashrrev_i32_e32 v251, 31, v250
	v_lshlrev_b64 v[250:251], 11, v[250:251]
	v_lshl_add_u64 v[250:251], v[164:165], 0, v[250:251]
	global_load_dwordx4 v[244:247], v[250:251], off
	s_nop 0
	global_load_dwordx4 v[248:251], v[250:251], off offset:256
	s_lshl_b32 s48, s34, 2
	s_ashr_i32 s49, s48, 31
	s_waitcnt vmcnt(8)
	v_lshlrev_b32_e32 v194, 16, v200
	v_add_f32_e32 v148, v148, v194
	v_and_b32_e32 v194, 0xffff0000, v200
	v_add_f32_e32 v149, v149, v194
	v_lshlrev_b32_e32 v194, 16, v201
	v_add_f32_e32 v150, v150, v194
	v_and_b32_e32 v194, 0xffff0000, v201
	v_add_f32_e32 v151, v151, v194
	v_lshlrev_b32_e32 v194, 16, v202
	v_add_f32_e32 v194, v144, v194
	v_and_b32_e32 v144, 0xffff0000, v202
	v_add_f32_e32 v195, v145, v144
	v_lshlrev_b32_e32 v144, 16, v203
	v_add_f32_e32 v200, v146, v144
	v_and_b32_e32 v144, 0xffff0000, v203
	v_add_f32_e32 v147, v147, v144
	v_mul_f32_e32 v144, v194, v194
	v_mul_f32_e32 v145, v195, v195
	v_fmac_f32_e32 v144, v148, v148
	v_fmac_f32_e32 v145, v149, v149
	v_add_f32_e32 v144, v144, v145
	v_mul_f32_e32 v145, v200, v200
	v_fmac_f32_e32 v145, v150, v150
	v_add_f32_e32 v144, v145, v144
	v_mul_f32_e32 v145, v147, v147
	v_fmac_f32_e32 v145, v151, v151
	v_add_f32_e32 v201, v145, v144
	v_cvt_pk_bf16_f32 v144, v148, v149
	v_lshl_add_u64 v[148:149], s[64:65], 0, v[192:193]
	v_lshl_add_u64 v[148:149], v[148:149], 0, v[184:185]
	v_cvt_pk_bf16_f32 v145, v150, v151
	v_cvt_pk_bf16_f32 v146, v194, v195
	v_cvt_pk_bf16_f32 v147, v200, v147
	global_store_dwordx4 v[148:149], v[144:147], off
	s_nop 1
	v_lshlrev_b32_e32 v144, 16, v204
	v_add_f32_e32 v140, v140, v144
	v_and_b32_e32 v144, 0xffff0000, v204
	v_add_f32_e32 v141, v141, v144
	v_lshlrev_b32_e32 v144, 16, v205
	v_add_f32_e32 v142, v142, v144
	v_and_b32_e32 v144, 0xffff0000, v205
	v_add_f32_e32 v143, v143, v144
	v_lshlrev_b32_e32 v144, 16, v206
	v_add_f32_e32 v144, v136, v144
	v_and_b32_e32 v136, 0xffff0000, v206
	v_add_f32_e32 v145, v137, v136
	v_lshlrev_b32_e32 v136, 16, v207
	v_add_f32_e32 v146, v138, v136
	v_and_b32_e32 v136, 0xffff0000, v207
	v_add_f32_e32 v139, v139, v136
	v_mul_f32_e32 v136, v144, v144
	v_fmac_f32_e32 v136, v140, v140
	v_mul_f32_e32 v137, v145, v145
	v_add_f32_e32 v136, v136, v201
	v_fmac_f32_e32 v137, v141, v141
	v_add_f32_e32 v136, v137, v136
	v_mul_f32_e32 v137, v146, v146
	v_fmac_f32_e32 v137, v142, v142
	v_add_f32_e32 v136, v137, v136
	v_mul_f32_e32 v137, v139, v139
	v_fmac_f32_e32 v137, v143, v143
	v_add_f32_e32 v147, v137, v136
	v_cvt_pk_bf16_f32 v136, v140, v141
	v_cvt_pk_bf16_f32 v137, v142, v143
	v_cvt_pk_bf16_f32 v138, v144, v145
	v_cvt_pk_bf16_f32 v139, v146, v139
	global_store_dwordx4 v[148:149], v[136:139], off offset:256
	s_nop 1
	v_and_b32_e32 v137, 64, v225
	v_xor_b32_e32 v136, 16, v225
	v_add_u32_e32 v137, 64, v137
	v_cmp_lt_i32_e32 vcc, v136, v137
	v_xor_b32_e32 v139, 32, v225
	s_nop 0
	v_cndmask_b32_e32 v136, v225, v136, vcc
	v_lshlrev_b32_e32 v136, 2, v136
	ds_bpermute_b32 v138, v136, v147
	v_cmp_lt_i32_e32 vcc, v139, v137
	s_waitcnt lgkmcnt(0)
	v_add_f32_e32 v138, v147, v138
	v_cndmask_b32_e32 v137, v225, v139, vcc
	v_lshlrev_b32_e32 v137, 2, v137
	ds_bpermute_b32 v139, v137, v138
	s_and_saveexec_b64 s[28:29], s[38:39]
	s_cbranch_execz .LBB0_103
	v_lshlrev_b64 v[140:141], 6, v[166:167]
	v_lshl_add_u64 v[140:141], s[62:63], 0, v[140:141]
	v_lshl_add_u64 v[140:141], s[48:49], 2, v[140:141]
	s_lshl_b32 s34, s9, 2
	v_lshl_add_u64 v[140:141], v[140:141], 0, s[34:35]
	s_waitcnt lgkmcnt(0)
	v_add_f32_e32 v138, v138, v139
	global_store_dword v[140:141], v138, off

.LBB0_109:
	s_or_b64 exec, exec, s[28:29]
	v_add_u32_e32 v98, 0x80, v166
	v_ashrrev_i32_e32 v99, 31, v98
	v_lshlrev_b64 v[104:105], 11, v[98:99]
	s_waitcnt lgkmcnt(0)
	v_add_u32_e32 v96, 0x90, v166
	v_ashrrev_i32_e32 v97, 31, v96
	v_add_u32_e32 v94, 0xa0, v166
	v_ashrrev_i32_e32 v95, 31, v94
	v_add_u32_e32 v92, 0xb0, v166
	v_ashrrev_i32_e32 v93, 31, v92
	s_waitcnt vmcnt(8)
	v_mov_b32_e32 v100, v208
	v_mov_b32_e32 v101, v209
	v_mov_b32_e32 v102, v210
	v_mov_b32_e32 v103, v211
	v_mov_b32_e32 v88, v212
	v_mov_b32_e32 v89, v213
	v_mov_b32_e32 v90, v214
	v_mov_b32_e32 v91, v215
	v_mov_b32_e32 v84, v216
	v_mov_b32_e32 v85, v217
	v_mov_b32_e32 v86, v218
	v_mov_b32_e32 v87, v219
	v_mov_b32_e32 v80, v232
	v_mov_b32_e32 v81, v233
	v_mov_b32_e32 v82, v234
	v_mov_b32_e32 v83, v235
	v_mov_b32_e32 v76, v236
	v_mov_b32_e32 v77, v237
	v_mov_b32_e32 v78, v238
	v_mov_b32_e32 v79, v239
	v_mov_b32_e32 v72, v240
	v_mov_b32_e32 v73, v241
	v_mov_b32_e32 v74, v242
	v_mov_b32_e32 v75, v243
	v_mov_b32_e32 v68, v244
	v_mov_b32_e32 v69, v245
	v_mov_b32_e32 v70, v246
	v_mov_b32_e32 v71, v247
	v_mov_b32_e32 v64, v248
	v_mov_b32_e32 v65, v249
	v_mov_b32_e32 v66, v250
	v_mov_b32_e32 v67, v251
	v_lshlrev_b32_e32 v106, 16, v100
	v_and_b32_e32 v100, 0xffff0000, v100
	v_add_f32_e32 v61, v61, v100
	v_lshlrev_b32_e32 v100, 16, v101
	v_add_f32_e32 v62, v62, v100
	v_and_b32_e32 v100, 0xffff0000, v101
	v_add_f32_e32 v63, v63, v100
	v_lshlrev_b32_e32 v100, 16, v102
	v_add_f32_e32 v56, v56, v100
	v_and_b32_e32 v100, 0xffff0000, v102
	v_add_f32_e32 v57, v57, v100
	v_lshlrev_b32_e32 v100, 16, v103
	v_add_f32_e32 v100, v58, v100
	v_and_b32_e32 v58, 0xffff0000, v103
	v_add_f32_e32 v60, v60, v106
	v_add_f32_e32 v101, v59, v58
	v_mul_f32_e32 v58, v56, v56
	v_mul_f32_e32 v59, v57, v57
	v_fmac_f32_e32 v58, v60, v60
	v_fmac_f32_e32 v59, v61, v61
	v_add_f32_e32 v58, v58, v59
	v_mul_f32_e32 v59, v100, v100
	v_fmac_f32_e32 v59, v62, v62
	v_add_f32_e32 v58, v59, v58
	v_mul_f32_e32 v59, v101, v101
	v_fmac_f32_e32 v59, v63, v63
	v_add_f32_e32 v102, v59, v58
	v_cvt_pk_bf16_f32 v58, v60, v61
	v_cvt_pk_bf16_f32 v59, v62, v63
	v_cvt_pk_bf16_f32 v60, v56, v57
	v_lshl_add_u64 v[56:57], s[64:65], 0, v[104:105]
	v_lshl_add_u64 v[56:57], v[162:163], 1, v[56:57]
	v_cvt_pk_bf16_f32 v61, v100, v101
	global_store_dwordx4 v[56:57], v[58:61], off
	s_nop 0
	v_lshlrev_b32_e32 v58, 16, v88
	v_add_f32_e32 v52, v52, v58
	v_and_b32_e32 v58, 0xffff0000, v88
	v_add_f32_e32 v53, v53, v58
	v_lshlrev_b32_e32 v58, 16, v89
	v_add_f32_e32 v54, v54, v58
	v_and_b32_e32 v58, 0xffff0000, v89
	v_add_f32_e32 v55, v55, v58
	v_lshlrev_b32_e32 v58, 16, v90
	v_add_f32_e32 v58, v48, v58
	v_and_b32_e32 v48, 0xffff0000, v90
	v_add_f32_e32 v59, v49, v48
	v_lshlrev_b32_e32 v48, 16, v91
	v_add_f32_e32 v60, v50, v48
	v_and_b32_e32 v48, 0xffff0000, v91
	v_add_f32_e32 v51, v51, v48
	v_mul_f32_e32 v48, v58, v58
	v_fmac_f32_e32 v48, v52, v52
	v_mul_f32_e32 v49, v59, v59
	v_add_f32_e32 v48, v48, v102
	v_fmac_f32_e32 v49, v53, v53
	v_add_f32_e32 v48, v49, v48
	v_mul_f32_e32 v49, v60, v60
	v_fmac_f32_e32 v49, v54, v54
	v_add_f32_e32 v48, v49, v48
	v_mul_f32_e32 v49, v51, v51
	v_fmac_f32_e32 v49, v55, v55
	v_add_f32_e32 v61, v49, v48
	v_cvt_pk_bf16_f32 v48, v52, v53
	v_cvt_pk_bf16_f32 v49, v54, v55
	v_cvt_pk_bf16_f32 v50, v58, v59
	v_cvt_pk_bf16_f32 v51, v60, v51
	global_store_dwordx4 v[56:57], v[48:51], off offset:256
	ds_bpermute_b32 v48, v136, v61
	s_waitcnt lgkmcnt(0)
	v_add_f32_e32 v48, v61, v48
	ds_bpermute_b32 v49, v137, v48
	s_and_saveexec_b64 s[28:29], s[38:39]
	s_cbranch_execz .LBB0_111
	v_lshlrev_b64 v[50:51], 6, v[98:99]
	v_lshl_add_u64 v[50:51], s[62:63], 0, v[50:51]
	v_lshl_add_u64 v[50:51], s[48:49], 2, v[50:51]
	s_lshl_b32 s34, s9, 2
	v_lshl_add_u64 v[50:51], v[50:51], 0, s[34:35]
	s_waitcnt lgkmcnt(0)
	v_add_f32_e32 v48, v48, v49
	global_store_dword v[50:51], v48, off
.LBB0_111:
	s_or_b64 exec, exec, s[28:29]
	v_lshlrev_b32_e32 v50, 16, v84
	v_add_f32_e32 v44, v44, v50
	v_and_b32_e32 v50, 0xffff0000, v84
	v_add_f32_e32 v45, v45, v50
	v_lshlrev_b32_e32 v50, 16, v85
	v_add_f32_e32 v46, v46, v50
	v_and_b32_e32 v50, 0xffff0000, v85
	v_add_f32_e32 v47, v47, v50
	v_lshlrev_b32_e32 v50, 16, v86
	v_add_f32_e32 v50, v40, v50
	v_and_b32_e32 v40, 0xffff0000, v86
	v_add_f32_e32 v51, v41, v40
	v_lshlrev_b32_e32 v40, 16, v87
	v_add_f32_e32 v52, v42, v40
	v_and_b32_e32 v40, 0xffff0000, v87
	v_add_f32_e32 v43, v43, v40
	v_mul_f32_e32 v40, v50, v50
	v_mul_f32_e32 v41, v51, v51
	v_fmac_f32_e32 v40, v44, v44
	v_fmac_f32_e32 v41, v45, v45
	v_add_f32_e32 v40, v40, v41
	v_mul_f32_e32 v41, v52, v52
	v_fmac_f32_e32 v41, v46, v46
	v_add_f32_e32 v40, v41, v40
	v_mul_f32_e32 v41, v43, v43
	v_fmac_f32_e32 v41, v47, v47
	v_add_f32_e32 v53, v41, v40
	v_cvt_pk_bf16_f32 v40, v44, v45
	v_lshlrev_b32_e32 v44, 16, v80
	v_add_f32_e32 v36, v36, v44
	v_and_b32_e32 v44, 0xffff0000, v80
	v_add_f32_e32 v37, v37, v44
	v_lshlrev_b32_e32 v44, 16, v81
	v_add_f32_e32 v44, v38, v44
	v_and_b32_e32 v38, 0xffff0000, v81
	v_add_f32_e32 v45, v39, v38
	v_lshlrev_b32_e32 v38, 16, v82
	v_cvt_pk_bf16_f32 v41, v46, v47
	v_add_f32_e32 v46, v32, v38
	v_and_b32_e32 v32, 0xffff0000, v82
	v_add_f32_e32 v47, v33, v32
	v_lshlrev_b32_e32 v32, 16, v83
	v_cvt_pk_bf16_f32 v42, v50, v51
	v_add_f32_e32 v50, v34, v32
	v_and_b32_e32 v32, 0xffff0000, v83
	v_add_f32_e32 v51, v35, v32
	v_mul_f32_e32 v32, v46, v46
	v_fmac_f32_e32 v32, v36, v36
	v_mul_f32_e32 v33, v47, v47
	v_add_f32_e32 v32, v32, v53
	v_fmac_f32_e32 v33, v37, v37
	v_add_f32_e32 v32, v33, v32
	v_mul_f32_e32 v33, v50, v50
	v_fmac_f32_e32 v33, v44, v44
	v_add_f32_e32 v32, v33, v32
	v_mul_f32_e32 v33, v51, v51
	v_fmac_f32_e32 v33, v45, v45
	v_add_f32_e32 v35, v33, v32
	v_cvt_pk_bf16_f32 v43, v52, v43
	ds_bpermute_b32 v52, v136, v35
	s_waitcnt lgkmcnt(1)
	v_lshlrev_b64 v[48:49], 10, v[96:97]
	v_lshl_add_u64 v[32:33], v[48:49], 1, s[64:65]
	v_lshl_add_u64 v[38:39], v[162:163], 1, v[32:33]
	global_store_dwordx4 v[38:39], v[40:43], off
	s_waitcnt lgkmcnt(0)
	v_add_f32_e32 v32, v35, v52
	ds_bpermute_b32 v33, v137, v32
	v_cvt_pk_bf16_f32 v34, v36, v37
	v_cvt_pk_bf16_f32 v35, v44, v45
	v_cvt_pk_bf16_f32 v36, v46, v47
	v_cvt_pk_bf16_f32 v37, v50, v51
	global_store_dwordx4 v[38:39], v[34:37], off offset:256
	s_and_saveexec_b64 s[28:29], s[38:39]
	s_cbranch_execz .LBB0_113
	v_lshlrev_b64 v[34:35], 6, v[96:97]
	v_lshl_add_u64 v[34:35], s[62:63], 0, v[34:35]
	v_lshl_add_u64 v[34:35], s[48:49], 2, v[34:35]
	s_lshl_b32 s34, s9, 2
	v_lshl_add_u64 v[34:35], v[34:35], 0, s[34:35]
	s_waitcnt lgkmcnt(0)
	v_add_f32_e32 v32, v32, v33
	global_store_dword v[34:35], v32, off
.LBB0_113:
	s_or_b64 exec, exec, s[28:29]
	v_lshlrev_b32_e32 v34, 16, v76
	v_add_f32_e32 v28, v28, v34
	v_and_b32_e32 v34, 0xffff0000, v76
	v_add_f32_e32 v29, v29, v34
	v_lshlrev_b32_e32 v34, 16, v77
	v_add_f32_e32 v30, v30, v34
	v_and_b32_e32 v34, 0xffff0000, v77
	v_add_f32_e32 v31, v31, v34
	v_lshlrev_b32_e32 v34, 16, v78
	v_add_f32_e32 v34, v24, v34
	v_and_b32_e32 v24, 0xffff0000, v78
	v_add_f32_e32 v35, v25, v24
	v_lshlrev_b32_e32 v24, 16, v79
	v_add_f32_e32 v36, v26, v24
	v_and_b32_e32 v24, 0xffff0000, v79
	v_add_f32_e32 v27, v27, v24
	v_mul_f32_e32 v24, v34, v34
	v_mul_f32_e32 v25, v35, v35
	v_fmac_f32_e32 v24, v28, v28
	v_fmac_f32_e32 v25, v29, v29
	v_add_f32_e32 v24, v24, v25
	v_mul_f32_e32 v25, v36, v36
	v_fmac_f32_e32 v25, v30, v30
	v_add_f32_e32 v24, v25, v24
	v_mul_f32_e32 v25, v27, v27
	v_fmac_f32_e32 v25, v31, v31
	v_add_f32_e32 v37, v25, v24
	v_cvt_pk_bf16_f32 v24, v28, v29
	v_lshlrev_b32_e32 v28, 16, v72
	v_add_f32_e32 v20, v20, v28
	v_and_b32_e32 v28, 0xffff0000, v72
	v_add_f32_e32 v21, v21, v28
	v_lshlrev_b32_e32 v28, 16, v73
	v_add_f32_e32 v28, v22, v28
	v_and_b32_e32 v22, 0xffff0000, v73
	v_add_f32_e32 v29, v23, v22
	v_lshlrev_b32_e32 v22, 16, v74
	v_cvt_pk_bf16_f32 v25, v30, v31
	v_add_f32_e32 v30, v16, v22
	v_and_b32_e32 v16, 0xffff0000, v74
	v_add_f32_e32 v31, v17, v16
	v_lshlrev_b32_e32 v16, 16, v75
	v_cvt_pk_bf16_f32 v26, v34, v35
	v_add_f32_e32 v34, v18, v16
	v_and_b32_e32 v16, 0xffff0000, v75
	v_add_f32_e32 v35, v19, v16
	v_mul_f32_e32 v16, v30, v30
	v_fmac_f32_e32 v16, v20, v20
	v_mul_f32_e32 v17, v31, v31
	v_add_f32_e32 v16, v16, v37
	v_fmac_f32_e32 v17, v21, v21
	v_add_f32_e32 v16, v17, v16
	v_mul_f32_e32 v17, v34, v34
	v_fmac_f32_e32 v17, v28, v28
	v_add_f32_e32 v16, v17, v16
	v_mul_f32_e32 v17, v35, v35
	v_fmac_f32_e32 v17, v29, v29
	v_add_f32_e32 v19, v17, v16
	v_cvt_pk_bf16_f32 v27, v36, v27
	ds_bpermute_b32 v36, v136, v19
	s_waitcnt lgkmcnt(1)
	v_lshlrev_b64 v[32:33], 10, v[94:95]
	v_lshl_add_u64 v[16:17], v[32:33], 1, s[64:65]
	v_lshl_add_u64 v[22:23], v[162:163], 1, v[16:17]
	global_store_dwordx4 v[22:23], v[24:27], off
	s_waitcnt lgkmcnt(0)
	v_add_f32_e32 v16, v19, v36
	ds_bpermute_b32 v17, v137, v16
	v_cvt_pk_bf16_f32 v18, v20, v21
	v_cvt_pk_bf16_f32 v19, v28, v29
	v_cvt_pk_bf16_f32 v20, v30, v31
	v_cvt_pk_bf16_f32 v21, v34, v35
	global_store_dwordx4 v[22:23], v[18:21], off offset:256
	s_and_saveexec_b64 s[28:29], s[38:39]
	s_cbranch_execz .LBB0_115
	v_lshlrev_b64 v[18:19], 6, v[94:95]
	v_lshl_add_u64 v[18:19], s[62:63], 0, v[18:19]
	v_lshl_add_u64 v[18:19], s[48:49], 2, v[18:19]
	s_lshl_b32 s34, s9, 2
	v_lshl_add_u64 v[18:19], v[18:19], 0, s[34:35]
	s_waitcnt lgkmcnt(0)
	v_add_f32_e32 v16, v16, v17
	global_store_dword v[18:19], v16, off
.LBB0_115:
	s_or_b64 exec, exec, s[28:29]
	v_lshlrev_b32_e32 v18, 16, v68
	v_add_f32_e32 v12, v12, v18
	v_and_b32_e32 v18, 0xffff0000, v68
	v_add_f32_e32 v13, v13, v18
	v_lshlrev_b32_e32 v18, 16, v69
	v_add_f32_e32 v14, v14, v18
	v_and_b32_e32 v18, 0xffff0000, v69
	v_add_f32_e32 v15, v15, v18
	v_lshlrev_b32_e32 v18, 16, v70
	v_add_f32_e32 v18, v8, v18
	v_and_b32_e32 v8, 0xffff0000, v70
	v_add_f32_e32 v19, v9, v8
	v_lshlrev_b32_e32 v8, 16, v71
	v_add_f32_e32 v20, v10, v8
	v_and_b32_e32 v8, 0xffff0000, v71
	v_add_f32_e32 v11, v11, v8
	v_mul_f32_e32 v8, v18, v18
	v_mul_f32_e32 v9, v19, v19
	v_fmac_f32_e32 v8, v12, v12
	v_fmac_f32_e32 v9, v13, v13
	v_add_f32_e32 v8, v8, v9
	v_mul_f32_e32 v9, v20, v20
	v_fmac_f32_e32 v9, v14, v14
	v_add_f32_e32 v8, v9, v8
	v_mul_f32_e32 v9, v11, v11
	v_fmac_f32_e32 v9, v15, v15
	v_add_f32_e32 v21, v9, v8
	v_cvt_pk_bf16_f32 v8, v12, v13
	v_lshlrev_b32_e32 v12, 16, v64
	v_add_f32_e32 v4, v4, v12
	v_and_b32_e32 v12, 0xffff0000, v64
	v_add_f32_e32 v5, v5, v12
	v_lshlrev_b32_e32 v12, 16, v65
	v_add_f32_e32 v12, v6, v12
	v_and_b32_e32 v6, 0xffff0000, v65
	v_add_f32_e32 v13, v7, v6
	v_lshlrev_b32_e32 v6, 16, v66
	v_cvt_pk_bf16_f32 v9, v14, v15
	v_add_f32_e32 v14, v0, v6
	v_and_b32_e32 v0, 0xffff0000, v66
	v_add_f32_e32 v15, v1, v0
	v_lshlrev_b32_e32 v0, 16, v67
	v_cvt_pk_bf16_f32 v10, v18, v19
	v_add_f32_e32 v18, v2, v0
	v_and_b32_e32 v0, 0xffff0000, v67
	v_add_f32_e32 v19, v3, v0
	v_mul_f32_e32 v0, v14, v14
	v_fmac_f32_e32 v0, v4, v4
	v_mul_f32_e32 v1, v15, v15
	v_add_f32_e32 v0, v0, v21
	v_fmac_f32_e32 v1, v5, v5
	v_add_f32_e32 v0, v1, v0
	v_mul_f32_e32 v1, v18, v18
	v_fmac_f32_e32 v1, v12, v12
	v_add_f32_e32 v0, v1, v0
	v_mul_f32_e32 v1, v19, v19
	v_fmac_f32_e32 v1, v13, v13
	v_add_f32_e32 v3, v1, v0
	v_cvt_pk_bf16_f32 v11, v20, v11
	ds_bpermute_b32 v20, v136, v3
	s_waitcnt lgkmcnt(1)
	v_lshlrev_b64 v[16:17], 10, v[92:93]
	v_lshl_add_u64 v[0:1], v[16:17], 1, s[64:65]
	v_lshl_add_u64 v[6:7], v[162:163], 1, v[0:1]
	global_store_dwordx4 v[6:7], v[8:11], off
	s_waitcnt lgkmcnt(0)
	v_add_f32_e32 v0, v3, v20
	ds_bpermute_b32 v1, v137, v0
	v_cvt_pk_bf16_f32 v2, v4, v5
	v_cvt_pk_bf16_f32 v3, v12, v13
	v_cvt_pk_bf16_f32 v4, v14, v15
	v_cvt_pk_bf16_f32 v5, v18, v19
	global_store_dwordx4 v[6:7], v[2:5], off offset:256
	s_and_saveexec_b64 s[28:29], s[38:39]
	s_cbranch_execz .LBB0_92
	v_lshlrev_b64 v[2:3], 6, v[92:93]
	v_lshl_add_u64 v[2:3], s[62:63], 0, v[2:3]
	v_lshl_add_u64 v[2:3], s[48:49], 2, v[2:3]
	s_lshl_b32 s34, s9, 2
	v_lshl_add_u64 v[2:3], v[2:3], 0, s[34:35]
	s_waitcnt lgkmcnt(0)
	v_add_f32_e32 v0, v0, v1
	global_store_dword v[2:3], v0, off
	s_branch .LBB0_92

.LBB0_129:
	s_ashr_i32 s2, s2, 3
	s_add_i32 s2, s6, s2
	s_ashr_i32 s3, s2, 31
	s_lshr_b32 s3, s3, 25
	s_add_i32 s3, s2, s3
	s_ashr_i32 s6, s3, 7
	s_lshl_b32 s6, s6, 3
	s_and_b32 s3, s3, 0xffffff80
	s_sub_i32 s2, s2, s3
	s_and_b32 s2, s2, 7
	s_add_i32 s54, s6, s2

.LBB0_145:
	s_ashr_i32 s20, s20, 3
	s_add_i32 s20, s24, s20
	s_ashr_i32 s21, s20, 31
	s_lshr_b32 s21, s21, 25
	s_add_i32 s21, s20, s21
	s_ashr_i32 s24, s21, 7
	s_lshl_b32 s24, s24, 3
	s_and_b32 s21, s21, 0xffffff80
	s_sub_i32 s20, s20, s21
	s_ashr_i32 s40, s20, 3
	s_and_b32 s20, s20, 7
	s_add_i32 s42, s24, s20

.LBB0_290:
	s_ashr_i32 s0, s20, 3
	s_add_i32 s0, s24, s0
	s_ashr_i32 s1, s0, 31
	s_lshr_b32 s1, s1, 22
	s_add_i32 s1, s0, s1
	s_ashr_i32 s20, s1, 10
	s_lshl_b32 s20, s20, 3
	s_and_b32 s1, s1, 0xfffffc00
	s_sub_i32 s1, s0, s1
	s_ashr_i32 s0, s1, 3
	s_and_b32 s1, s1, 7
	s_add_i32 s40, s20, s1
